# P1 GEMM: accumulator zeroing removed, first K-iteration peeled with srcC=0
# baseline (speedup 1.0000x reference)
; #define PG8_STAGE(bufoff, gbase, voff) do { _Pragma("unroll") for (int _i = 0; _i < 2; ++_i) \
;         __builtin_amdgcn_global_load_lds((const unsigned*)((const char*)(gbase) + (voff)[_i]), (PG8_LAS unsigned*)(lds + (bufoff) + ldsw + _i * 8192), 16, 0, 0); } while (0)
; #define PG8_LDA(dst, b, h) do { _Pragma("unroll") for (int m = 0; m < 4; ++m) _Pragma("unroll") for (int k = 0; k < 2; ++k) dst[m][k] = *(const PG8_LAS bf16x8*)(lds + PG8_SA(b, h) + aoff + m * 2048 + k * 1024); } while (0)
; #define PG8_LDB(dst, b, h) do { _Pragma("unroll") for (int n = 0; n < 2; ++n) _Pragma("unroll") for (int k = 0; k < 2; ++k) dst[n][k] = *(const PG8_LAS bf16x8*)(lds + PG8_SB(b, h) + boff + n * 2048 + k * 1024); } while (0)
; #define PG8_MMA(ai, bj, At, Bt) do { __builtin_amdgcn_s_setprio(1); _Pragma("unroll") for (int m = 0; m < 4; ++m) _Pragma("unroll") for (int n = 0; n < 2; ++n) _Pragma("unroll") for (int k = 0; k < 2; ++k) \
;         acc[ai][bj][m][n] = __builtin_amdgcn_mfma_f32_16x16x32_bf16(Bt[n][k], At[m][k], acc[ai][bj][m][n], 0, 0, 0); __builtin_amdgcn_s_setprio(0); } while (0)
; template <class Epi, class Sched, bool ALIGN_EPI = false, bool SP2 = false>
; __device__ __forceinline__ void gemm_phase(PG8_LAS unsigned char* lds, const Gemm g, const Sched& S, const Epi& E, int wid_in) {
;     ...
;         const char* nA = has_next ? (const char*)g.A + (size_t)nxt.pm * tstep : cA; const char* nB = has_next ? (const char*)g.Bt + (size_t)nxt.pn * tstep : cB;
;         for (int t = 0; t < nt; t += 2) {
;             const bool last = (t == nt - 2);
;             if constexpr (Epi::HAS_MID) { if (t == nt / 2) E.mid(acc, cur, wr, wc, fr, fq); }
;             const char* a1 = cA + (size_t)(t + 1) * kstep;
;             const char* a2 = last ? nA : cA + (size_t)(t + 2) * kstep; const char* b2 = last ? nB : cB + (size_t)(t + 2) * kstep;
;             const char* a3 = a2 + kstep; const char* b3 = b2 + kstep;
;             if (last && has_next) S.a_ready(nxt);
;             if constexpr (SP2) {
;             PG8_LDB(B0, 0, 0); PG8_LDB(B1, 0, 1); PG8_SCHED; PG8_LDA(At, 0, 0); PG8_STAGE(PG8_SA(1, 1), a1 + hstep, voffA);
;             PG8_WAIT_V(8); PG8_WAIT_L(0); PG8_BAR; PG8_MMA(0, 0, At, B0); PG8_MMA(0, 1, At, B1); PG8_BAR; PG8_SCHED;
;             PG8_LDA(At, 0, 1); PG8_STAGE(PG8_SB(0, 0), b2, voffB); PG8_STAGE(PG8_SB(0, 1), b2 + hstep, voffB); PG8_STAGE(PG8_SA(0, 0), a2, voffA);
.LBB0_226:
	s_ashr_i32 s83, s82, 31
	s_lshl_b64 s[84:85], s[82:83], 19
	s_add_u32 s84, s8, s84
	s_addc_u32 s85, s9, s85
	s_and_b64 s[86:87], s[0:1], exec
	s_cselect_b32 s3, s85, s69
	s_cselect_b32 s5, s84, s68
	s_ashr_i32 s81, s80, 31
	s_lshl_b64 s[86:87], s[80:81], 19
	s_add_u32 s86, s13, s86
	s_addc_u32 s87, s33, s87
	s_and_b64 s[90:91], s[0:1], exec
	s_cselect_b32 s81, s87, s89
	s_cselect_b32 s83, s86, s88
	s_add_u32 s68, s68, 0x40080
	s_addc_u32 s69, s69, 0
	s_add_u32 s92, s88, 0x100
	s_addc_u32 s93, s89, 0
	s_mov_b32 s94, -2
	ds_read_b128 v[128:131], v171
	ds_read_b128 v[132:135], v171 offset:1024
	ds_read_b128 v[158:161], v171 offset:2048
	ds_read_b128 v[162:165], v171 offset:3072
	ds_read_b128 v[174:177], v172
	ds_read_b128 v[178:181], v172 offset:1024
	ds_read_b128 v[182:185], v172 offset:2048
	ds_read_b128 v[186:189], v172 offset:3072
	s_add_u32 s88, s68, 0xfffc0080
	s_addc_u32 s89, s69, -1
	s_cmp_eq_u32 s94, 12
	s_cselect_b32 s91, s3, s89
	s_cselect_b32 s90, s5, s88
	s_cselect_b32 s89, s81, s93
	s_cselect_b32 s88, s83, s92
	v_lshl_add_u64 v[166:167], s[68:69], 0, v[150:151]
	s_add_i32 m0, s34, 0xc000
	ds_read_b128 v[190:193], v173
	ds_read_b128 v[194:197], v173 offset:1024
	ds_read_b128 v[198:201], v173 offset:2048
	ds_read_b128 v[202:205], v173 offset:3072
	ds_read_b128 v[206:209], v173 offset:4096
	ds_read_b128 v[210:213], v173 offset:5120
	ds_read_b128 v[214:217], v173 offset:6144
	ds_read_b128 v[218:221], v173 offset:7168
	global_load_lds_dwordx4 v[166:167], off
	v_lshl_add_u64 v[166:167], s[68:69], 0, v[152:153]
	s_add_i32 m0, s34, 0xe000
	s_nop 0
	global_load_lds_dwordx4 v[166:167], off
	s_waitcnt vmcnt(8)
	s_waitcnt lgkmcnt(0)
	s_barrier
	s_setprio 1
	s_waitcnt lgkmcnt(0)
	v_mfma_f32_16x16x32_bf16 v[124:127], v[128:131], v[190:193], 0
	v_mfma_f32_16x16x32_bf16 v[120:123], v[158:161], v[190:193], 0
	v_mfma_f32_16x16x32_bf16 v[108:111], v[128:131], v[198:201], 0
	v_mfma_f32_16x16x32_bf16 v[104:107], v[158:161], v[198:201], 0
	v_mfma_f32_16x16x32_bf16 v[92:95], v[128:131], v[206:209], 0
	v_mfma_f32_16x16x32_bf16 v[88:91], v[158:161], v[206:209], 0
	v_mfma_f32_16x16x32_bf16 v[76:79], v[128:131], v[214:217], 0
	v_mfma_f32_16x16x32_bf16 v[72:75], v[158:161], v[214:217], 0
	v_mfma_f32_16x16x32_bf16 v[124:127], v[132:135], v[194:197], v[124:127]
	v_mfma_f32_16x16x32_bf16 v[120:123], v[162:165], v[194:197], v[120:123]
	v_mfma_f32_16x16x32_bf16 v[108:111], v[132:135], v[202:205], v[108:111]
	v_mfma_f32_16x16x32_bf16 v[104:107], v[162:165], v[202:205], v[104:107]
	v_mfma_f32_16x16x32_bf16 v[92:95], v[132:135], v[210:213], v[92:95]
	v_mfma_f32_16x16x32_bf16 v[88:91], v[162:165], v[210:213], v[88:91]
	v_mfma_f32_16x16x32_bf16 v[76:79], v[132:135], v[218:221], v[76:79]
	v_mfma_f32_16x16x32_bf16 v[72:75], v[162:165], v[218:221], v[72:75]
	s_setprio 0
	s_setprio 1
	v_mfma_f32_16x16x32_bf16 v[116:119], v[174:177], v[190:193], 0
	v_mfma_f32_16x16x32_bf16 v[112:115], v[182:185], v[190:193], 0
	v_mfma_f32_16x16x32_bf16 v[100:103], v[174:177], v[198:201], 0
	v_mfma_f32_16x16x32_bf16 v[96:99], v[182:185], v[198:201], 0
	v_mfma_f32_16x16x32_bf16 v[84:87], v[174:177], v[206:209], 0
	v_mfma_f32_16x16x32_bf16 v[80:83], v[182:185], v[206:209], 0
	v_mfma_f32_16x16x32_bf16 v[68:71], v[174:177], v[214:217], 0
	v_mfma_f32_16x16x32_bf16 v[64:67], v[182:185], v[214:217], 0
	v_mfma_f32_16x16x32_bf16 v[116:119], v[178:181], v[194:197], v[116:119]
	v_mfma_f32_16x16x32_bf16 v[112:115], v[186:189], v[194:197], v[112:115]
	v_mfma_f32_16x16x32_bf16 v[100:103], v[178:181], v[202:205], v[100:103]
	v_mfma_f32_16x16x32_bf16 v[96:99], v[186:189], v[202:205], v[96:99]
	v_mfma_f32_16x16x32_bf16 v[84:87], v[178:181], v[210:213], v[84:87]
	v_mfma_f32_16x16x32_bf16 v[80:83], v[186:189], v[210:213], v[80:83]
	v_mfma_f32_16x16x32_bf16 v[68:71], v[178:181], v[218:221], v[68:71]
	v_mfma_f32_16x16x32_bf16 v[64:67], v[186:189], v[218:221], v[64:67]
	s_setprio 0
	s_barrier
	s_add_i32 s95, s70, s12
	v_lshl_add_u64 v[166:167], s[88:89], 0, v[138:139]
	s_mov_b32 m0, s95
	ds_read_b128 v[190:193], v173 offset:16384
	ds_read_b128 v[194:197], v173 offset:17408
	ds_read_b128 v[198:201], v173 offset:18432
	ds_read_b128 v[202:205], v173 offset:19456
	ds_read_b128 v[206:209], v173 offset:20480
	ds_read_b128 v[210:213], v173 offset:21504
	ds_read_b128 v[214:217], v173 offset:22528
	ds_read_b128 v[218:221], v173 offset:23552
	global_load_lds_dwordx4 v[166:167], off
	s_add_i32 m0, s95, 0x2000
	s_add_u32 vcc_lo, s88, 0x40000
	v_lshl_add_u64 v[222:223], s[88:89], 0, v[142:143]
	s_addc_u32 vcc_hi, s89, 0
	s_add_i32 s95, s71, s12
	global_load_lds_dwordx4 v[222:223], off
	v_lshl_add_u64 v[224:225], vcc, 0, v[138:139]
	s_mov_b32 m0, s95
	v_lshl_add_u64 v[226:227], s[90:91], 0, v[140:141]
	global_load_lds_dwordx4 v[224:225], off
	v_lshl_add_u64 v[224:225], vcc, 0, v[142:143]
	s_add_i32 m0, s95, 0x2000
	s_nop 0
	global_load_lds_dwordx4 v[224:225], off
	v_lshl_add_u64 v[224:225], s[90:91], 0, v[136:137]
	s_mov_b32 m0, s34
	s_nop 0
	global_load_lds_dwordx4 v[224:225], off
	s_mov_b32 m0, s35
	s_nop 0
	global_load_lds_dwordx4 v[226:227], off
	s_waitcnt vmcnt(8)
	s_waitcnt lgkmcnt(0)
	s_barrier
; #define PG8_STAGE(bufoff, gbase, voff) do { _Pragma("unroll") for (int _i = 0; _i < 2; ++_i) \
;         __builtin_amdgcn_global_load_lds((const unsigned*)((const char*)(gbase) + (voff)[_i]), (PG8_LAS unsigned*)(lds + (bufoff) + ldsw + _i * 8192), 16, 0, 0); } while (0)
; #define PG8_LDA(dst, b, h) do { _Pragma("unroll") for (int m = 0; m < 4; ++m) _Pragma("unroll") for (int k = 0; k < 2; ++k) dst[m][k] = *(const PG8_LAS bf16x8*)(lds + PG8_SA(b, h) + aoff + m * 2048 + k * 1024); } while (0)
; #define PG8_LDB(dst, b, h) do { _Pragma("unroll") for (int n = 0; n < 2; ++n) _Pragma("unroll") for (int k = 0; k < 2; ++k) dst[n][k] = *(const PG8_LAS bf16x8*)(lds + PG8_SB(b, h) + boff + n * 2048 + k * 1024); } while (0)
; #define PG8_MMA(ai, bj, At, Bt) do { __builtin_amdgcn_s_setprio(1); _Pragma("unroll") for (int m = 0; m < 4; ++m) _Pragma("unroll") for (int n = 0; n < 2; ++n) _Pragma("unroll") for (int k = 0; k < 2; ++k) \
;         acc[ai][bj][m][n] = __builtin_amdgcn_mfma_f32_16x16x32_bf16(Bt[n][k], At[m][k], acc[ai][bj][m][n], 0, 0, 0); __builtin_amdgcn_s_setprio(0); } while (0)
; #define PG8_WAIT_V(n) asm volatile("s_waitcnt vmcnt(" #n ")" ::: "memory")
; #define PG8_WAIT_L(n) asm volatile("s_waitcnt lgkmcnt(" #n ")" ::: "memory")
; #define PG8_BAR __builtin_amdgcn_s_barrier()
; #define PG8_SCHED __builtin_amdgcn_sched_barrier(0)
; template <class Epi, class Sched, bool ALIGN_EPI = false, bool SP2 = false>
; __device__ __forceinline__ void gemm_phase(PG8_LAS unsigned char* lds, const Gemm g, const Sched& S, const Epi& E, int wid_in) {
;     ...
;             PG8_WAIT_V(8); PG8_WAIT_L(0); PG8_BAR; PG8_MMA(0, 0, At, B0); PG8_MMA(0, 1, At, B1); PG8_BAR; PG8_SCHED;
;             PG8_LDA(At, 0, 1); PG8_STAGE(PG8_SB(0, 0), b2, voffB); PG8_STAGE(PG8_SB(0, 1), b2 + hstep, voffB); PG8_STAGE(PG8_SA(0, 0), a2, voffA);
;             PG8_WAIT_V(8); PG8_WAIT_L(0); PG8_BAR; PG8_MMA(1, 0, At, B0); PG8_MMA(1, 1, At, B1); PG8_BAR; PG8_SCHED;
;             PG8_LDB(B0, 1, 0); PG8_LDB(B1, 1, 1); PG8_SCHED; PG8_LDA(At, 1, 0); PG8_STAGE(PG8_SA(0, 1), a2 + hstep, voffA);
;             PG8_WAIT_V(8); PG8_WAIT_L(0); PG8_BAR; PG8_MMA(0, 0, At, B0); PG8_MMA(0, 1, At, B1); PG8_BAR; PG8_SCHED;
	s_setprio 1
	s_waitcnt lgkmcnt(0)
	v_mfma_f32_16x16x32_bf16 v[60:63], v[128:131], v[190:193], 0
	v_mfma_f32_16x16x32_bf16 v[56:59], v[158:161], v[190:193], 0
	v_mfma_f32_16x16x32_bf16 v[44:47], v[128:131], v[198:201], 0
	v_mfma_f32_16x16x32_bf16 v[40:43], v[158:161], v[198:201], 0
	v_mfma_f32_16x16x32_bf16 v[28:31], v[128:131], v[206:209], 0
	v_mfma_f32_16x16x32_bf16 v[24:27], v[158:161], v[206:209], 0
	v_mfma_f32_16x16x32_bf16 v[12:15], v[128:131], v[214:217], 0
	v_mfma_f32_16x16x32_bf16 v[8:11], v[158:161], v[214:217], 0
	v_mfma_f32_16x16x32_bf16 v[60:63], v[132:135], v[194:197], v[60:63]
	v_mfma_f32_16x16x32_bf16 v[56:59], v[162:165], v[194:197], v[56:59]
	v_mfma_f32_16x16x32_bf16 v[44:47], v[132:135], v[202:205], v[44:47]
	v_mfma_f32_16x16x32_bf16 v[40:43], v[162:165], v[202:205], v[40:43]
	v_mfma_f32_16x16x32_bf16 v[28:31], v[132:135], v[210:213], v[28:31]
	v_mfma_f32_16x16x32_bf16 v[24:27], v[162:165], v[210:213], v[24:27]
	v_mfma_f32_16x16x32_bf16 v[12:15], v[132:135], v[218:221], v[12:15]
	v_mfma_f32_16x16x32_bf16 v[8:11], v[162:165], v[218:221], v[8:11]
	s_setprio 0
	s_setprio 1
	v_mfma_f32_16x16x32_bf16 v[52:55], v[174:177], v[190:193], 0
	v_mfma_f32_16x16x32_bf16 v[48:51], v[182:185], v[190:193], 0
	v_mfma_f32_16x16x32_bf16 v[36:39], v[174:177], v[198:201], 0
	v_mfma_f32_16x16x32_bf16 v[32:35], v[182:185], v[198:201], 0
	v_mfma_f32_16x16x32_bf16 v[20:23], v[174:177], v[206:209], 0
	v_mfma_f32_16x16x32_bf16 v[16:19], v[182:185], v[206:209], 0
	v_mfma_f32_16x16x32_bf16 v[4:7], v[174:177], v[214:217], 0
	v_mfma_f32_16x16x32_bf16 v[0:3], v[182:185], v[214:217], 0
	v_mfma_f32_16x16x32_bf16 v[52:55], v[178:181], v[194:197], v[52:55]
	v_mfma_f32_16x16x32_bf16 v[48:51], v[186:189], v[194:197], v[48:51]
	v_mfma_f32_16x16x32_bf16 v[36:39], v[178:181], v[202:205], v[36:39]
	v_mfma_f32_16x16x32_bf16 v[32:35], v[186:189], v[202:205], v[32:35]
	v_mfma_f32_16x16x32_bf16 v[20:23], v[178:181], v[210:213], v[20:23]
	v_mfma_f32_16x16x32_bf16 v[16:19], v[186:189], v[210:213], v[16:19]
	v_mfma_f32_16x16x32_bf16 v[4:7], v[178:181], v[218:221], v[4:7]
	v_mfma_f32_16x16x32_bf16 v[0:3], v[186:189], v[218:221], v[0:3]
	s_setprio 0
	s_barrier
	s_add_i32 s95, 0, 0x18000
	v_add_u32_e32 v144, s95, v169
	s_add_i32 vcc_lo, 0, 0x1c000
	ds_read_b128 v[128:131], v144
	ds_read_b128 v[132:135], v144 offset:1024
	ds_read_b128 v[158:161], v144 offset:2048
	ds_read_b128 v[162:165], v144 offset:3072
	v_add_u32_e32 v144, vcc_lo, v169
	ds_read_b128 v[174:177], v144
	ds_read_b128 v[178:181], v144 offset:1024
	ds_read_b128 v[182:185], v144 offset:2048
	ds_read_b128 v[186:189], v144 offset:3072
	s_add_u32 s90, s90, 0x40000
	s_addc_u32 s91, s91, 0
	s_mov_b32 m0, s61
	v_lshl_add_u64 v[228:229], s[90:91], 0, v[136:137]
	ds_read_b128 v[190:193], v173 offset:32768
	ds_read_b128 v[194:197], v173 offset:33792
	ds_read_b128 v[198:201], v173 offset:34816
	ds_read_b128 v[202:205], v173 offset:35840
	ds_read_b128 v[206:209], v173 offset:36864
	ds_read_b128 v[210:213], v173 offset:37888
	ds_read_b128 v[214:217], v173 offset:38912
	ds_read_b128 v[218:221], v173 offset:39936
	global_load_lds_dwordx4 v[228:229], off
	v_lshl_add_u64 v[228:229], s[90:91], 0, v[140:141]
	s_mov_b32 m0, s62
	s_nop 0
	global_load_lds_dwordx4 v[228:229], off
	s_waitcnt vmcnt(8)
	s_waitcnt lgkmcnt(0)
	s_barrier
	s_setprio 1
	s_waitcnt lgkmcnt(0)
	v_mfma_f32_16x16x32_bf16 v[124:127], v[128:131], v[190:193], v[124:127]
	v_mfma_f32_16x16x32_bf16 v[120:123], v[158:161], v[190:193], v[120:123]
	v_mfma_f32_16x16x32_bf16 v[108:111], v[128:131], v[198:201], v[108:111]
	v_mfma_f32_16x16x32_bf16 v[104:107], v[158:161], v[198:201], v[104:107]
	v_mfma_f32_16x16x32_bf16 v[92:95], v[128:131], v[206:209], v[92:95]
	v_mfma_f32_16x16x32_bf16 v[88:91], v[158:161], v[206:209], v[88:91]
	v_mfma_f32_16x16x32_bf16 v[76:79], v[128:131], v[214:217], v[76:79]
	v_mfma_f32_16x16x32_bf16 v[72:75], v[158:161], v[214:217], v[72:75]
	v_mfma_f32_16x16x32_bf16 v[124:127], v[132:135], v[194:197], v[124:127]
	v_mfma_f32_16x16x32_bf16 v[120:123], v[162:165], v[194:197], v[120:123]
	v_mfma_f32_16x16x32_bf16 v[108:111], v[132:135], v[202:205], v[108:111]
	v_mfma_f32_16x16x32_bf16 v[104:107], v[162:165], v[202:205], v[104:107]
	v_mfma_f32_16x16x32_bf16 v[92:95], v[132:135], v[210:213], v[92:95]
	v_mfma_f32_16x16x32_bf16 v[88:91], v[162:165], v[210:213], v[88:91]
	v_mfma_f32_16x16x32_bf16 v[76:79], v[132:135], v[218:221], v[76:79]
	v_mfma_f32_16x16x32_bf16 v[72:75], v[162:165], v[218:221], v[72:75]
	s_setprio 0
	s_setprio 1
	v_mfma_f32_16x16x32_bf16 v[116:119], v[174:177], v[190:193], v[116:119]
	v_mfma_f32_16x16x32_bf16 v[112:115], v[182:185], v[190:193], v[112:115]
	v_mfma_f32_16x16x32_bf16 v[100:103], v[174:177], v[198:201], v[100:103]
	v_mfma_f32_16x16x32_bf16 v[96:99], v[182:185], v[198:201], v[96:99]
	v_mfma_f32_16x16x32_bf16 v[84:87], v[174:177], v[206:209], v[84:87]
	v_mfma_f32_16x16x32_bf16 v[80:83], v[182:185], v[206:209], v[80:83]
	v_mfma_f32_16x16x32_bf16 v[68:71], v[174:177], v[214:217], v[68:71]
	v_mfma_f32_16x16x32_bf16 v[64:67], v[182:185], v[214:217], v[64:67]
	v_mfma_f32_16x16x32_bf16 v[116:119], v[178:181], v[194:197], v[116:119]
	v_mfma_f32_16x16x32_bf16 v[112:115], v[186:189], v[194:197], v[112:115]
	v_mfma_f32_16x16x32_bf16 v[100:103], v[178:181], v[202:205], v[100:103]
	v_mfma_f32_16x16x32_bf16 v[96:99], v[186:189], v[202:205], v[96:99]
	v_mfma_f32_16x16x32_bf16 v[84:87], v[178:181], v[210:213], v[84:87]
	v_mfma_f32_16x16x32_bf16 v[80:83], v[186:189], v[210:213], v[80:83]
	v_mfma_f32_16x16x32_bf16 v[68:71], v[178:181], v[218:221], v[68:71]
	v_mfma_f32_16x16x32_bf16 v[64:67], v[186:189], v[218:221], v[64:67]
	s_setprio 0
	s_barrier
; #define PG8_STAGE(bufoff, gbase, voff) do { _Pragma("unroll") for (int _i = 0; _i < 2; ++_i) \
;         __builtin_amdgcn_global_load_lds((const unsigned*)((const char*)(gbase) + (voff)[_i]), (PG8_LAS unsigned*)(lds + (bufoff) + ldsw + _i * 8192), 16, 0, 0); } while (0)
; #define PG8_LDA(dst, b, h) do { _Pragma("unroll") for (int m = 0; m < 4; ++m) _Pragma("unroll") for (int k = 0; k < 2; ++k) dst[m][k] = *(const PG8_LAS bf16x8*)(lds + PG8_SA(b, h) + aoff + m * 2048 + k * 1024); } while (0)
; #define PG8_MMA(ai, bj, At, Bt) do { __builtin_amdgcn_s_setprio(1); _Pragma("unroll") for (int m = 0; m < 4; ++m) _Pragma("unroll") for (int n = 0; n < 2; ++n) _Pragma("unroll") for (int k = 0; k < 2; ++k) \
;         acc[ai][bj][m][n] = __builtin_amdgcn_mfma_f32_16x16x32_bf16(Bt[n][k], At[m][k], acc[ai][bj][m][n], 0, 0, 0); __builtin_amdgcn_s_setprio(0); } while (0)
; #define PG8_WAIT_V(n) asm volatile("s_waitcnt vmcnt(" #n ")" ::: "memory")
; #define PG8_WAIT_L(n) asm volatile("s_waitcnt lgkmcnt(" #n ")" ::: "memory")
; #define PG8_BAR __builtin_amdgcn_s_barrier()
; #define PG8_SCHED __builtin_amdgcn_sched_barrier(0)
; template <class Epi, class Sched, bool ALIGN_EPI = false, bool SP2 = false>
; __device__ __forceinline__ void gemm_phase(PG8_LAS unsigned char* lds, const Gemm g, const Sched& S, const Epi& E, int wid_in) {
;     ...
;             PG8_LDA(At, 1, 1); PG8_STAGE(PG8_SB(1, 0), b3, voffB); PG8_STAGE(PG8_SB(1, 1), b3 + hstep, voffB); PG8_STAGE(PG8_SA(1, 0), a3, voffA);
;             PG8_WAIT_V(8); PG8_WAIT_L(0); PG8_BAR; PG8_MMA(1, 0, At, B0); PG8_MMA(1, 1, At, B1); PG8_BAR; PG8_SCHED;
	s_add_i32 s90, s95, s12
	v_lshl_add_u64 v[166:167], v[166:167], 0, s[74:75]
	s_mov_b32 m0, s90
	ds_read_b128 v[190:193], v173 offset:49152
	ds_read_b128 v[194:197], v173 offset:50176
	ds_read_b128 v[198:201], v173 offset:51200
	ds_read_b128 v[202:205], v173 offset:52224
	ds_read_b128 v[206:209], v173 offset:53248
	ds_read_b128 v[210:213], v173 offset:54272
	ds_read_b128 v[214:217], v173 offset:55296
	ds_read_b128 v[218:221], v173 offset:56320
	global_load_lds_dwordx4 v[166:167], off
	s_add_i32 m0, s90, 0x2000
	s_add_u32 s88, s88, 0x40080
	v_lshl_add_u64 v[166:167], v[222:223], 0, s[74:75]
	s_addc_u32 s89, s89, 0
	s_add_i32 s90, vcc_lo, s12
	global_load_lds_dwordx4 v[166:167], off
	v_lshl_add_u64 v[166:167], s[88:89], 0, v[138:139]
	s_mov_b32 m0, s90
	s_nop 0
	global_load_lds_dwordx4 v[166:167], off
	v_lshl_add_u64 v[166:167], s[88:89], 0, v[142:143]
	s_add_i32 m0, s90, 0x2000
	s_nop 0
	global_load_lds_dwordx4 v[166:167], off
	v_lshl_add_u64 v[166:167], v[224:225], 0, s[74:75]
	s_mov_b32 m0, s64
	s_nop 0
	global_load_lds_dwordx4 v[166:167], off
	v_lshl_add_u64 v[166:167], v[226:227], 0, s[74:75]
	s_mov_b32 m0, s65
	s_nop 0
	global_load_lds_dwordx4 v[166:167], off
	s_waitcnt vmcnt(8)
	s_waitcnt lgkmcnt(0)
	s_barrier
	s_setprio 1
	s_waitcnt lgkmcnt(0)
	v_mfma_f32_16x16x32_bf16 v[60:63], v[128:131], v[190:193], v[60:63]
	v_mfma_f32_16x16x32_bf16 v[56:59], v[158:161], v[190:193], v[56:59]
	v_mfma_f32_16x16x32_bf16 v[44:47], v[128:131], v[198:201], v[44:47]
	v_mfma_f32_16x16x32_bf16 v[40:43], v[158:161], v[198:201], v[40:43]
	v_mfma_f32_16x16x32_bf16 v[28:31], v[128:131], v[206:209], v[28:31]
	v_mfma_f32_16x16x32_bf16 v[24:27], v[158:161], v[206:209], v[24:27]
	v_mfma_f32_16x16x32_bf16 v[12:15], v[128:131], v[214:217], v[12:15]
	v_mfma_f32_16x16x32_bf16 v[8:11], v[158:161], v[214:217], v[8:11]
	v_mfma_f32_16x16x32_bf16 v[60:63], v[132:135], v[194:197], v[60:63]
	v_mfma_f32_16x16x32_bf16 v[56:59], v[162:165], v[194:197], v[56:59]
	v_mfma_f32_16x16x32_bf16 v[44:47], v[132:135], v[202:205], v[44:47]
	v_mfma_f32_16x16x32_bf16 v[40:43], v[162:165], v[202:205], v[40:43]
	v_mfma_f32_16x16x32_bf16 v[28:31], v[132:135], v[210:213], v[28:31]
	v_mfma_f32_16x16x32_bf16 v[24:27], v[162:165], v[210:213], v[24:27]
	v_mfma_f32_16x16x32_bf16 v[12:15], v[132:135], v[218:221], v[12:15]
	v_mfma_f32_16x16x32_bf16 v[8:11], v[162:165], v[218:221], v[8:11]
	s_setprio 0
	s_setprio 1
	v_mfma_f32_16x16x32_bf16 v[52:55], v[174:177], v[190:193], v[52:55]
	v_mfma_f32_16x16x32_bf16 v[48:51], v[182:185], v[190:193], v[48:51]
	v_mfma_f32_16x16x32_bf16 v[36:39], v[174:177], v[198:201], v[36:39]
	v_mfma_f32_16x16x32_bf16 v[32:35], v[182:185], v[198:201], v[32:35]
	v_mfma_f32_16x16x32_bf16 v[20:23], v[174:177], v[206:209], v[20:23]
	v_mfma_f32_16x16x32_bf16 v[16:19], v[182:185], v[206:209], v[16:19]
	v_mfma_f32_16x16x32_bf16 v[4:7], v[174:177], v[214:217], v[4:7]
	v_mfma_f32_16x16x32_bf16 v[0:3], v[182:185], v[214:217], v[0:3]
	v_mfma_f32_16x16x32_bf16 v[52:55], v[178:181], v[194:197], v[52:55]
	v_mfma_f32_16x16x32_bf16 v[48:51], v[186:189], v[194:197], v[48:51]
	v_mfma_f32_16x16x32_bf16 v[36:39], v[178:181], v[202:205], v[36:39]
	v_mfma_f32_16x16x32_bf16 v[32:35], v[186:189], v[202:205], v[32:35]
	v_mfma_f32_16x16x32_bf16 v[20:23], v[178:181], v[210:213], v[20:23]
	v_mfma_f32_16x16x32_bf16 v[16:19], v[186:189], v[210:213], v[16:19]
	v_mfma_f32_16x16x32_bf16 v[4:7], v[178:181], v[218:221], v[4:7]
	v_mfma_f32_16x16x32_bf16 v[0:3], v[186:189], v[218:221], v[0:3]
	s_setprio 0
	s_barrier
	s_add_i32 s94, s94, 2
	s_add_u32 s68, s68, 0x100
	s_addc_u32 s69, s69, 0
	s_add_u32 s92, s92, 0x100
	s_addc_u32 s93, s93, 0
	s_cmp_gt_u32 s94, 13
